# v47 plus: x to bf16 row-conversion prologue keeps the next row's loads in flight during the current row's reduction and stores (vmcnt ladder replaced by a pre-loop wait and one counted wait before the
# speedup vs baseline: 1.0061x; 1.0061x over previous
.LBB0_67:
	s_cmp_lt_i32 s58, 0x8000
	s_cselect_b64 s[6:7], -1, 0
	v_writelane_b32 v252, s6, 18
	s_and_b64 vcc, exec, s[6:7]
	v_lshlrev_b32_e32 v164, 4, v219
	v_writelane_b32 v252, s7, 19
	v_writelane_b32 v252, s12, 20
	v_mbcnt_lo_u32_b32 v38, -1, 0
	s_nop 0
	v_writelane_b32 v252, s13, 21
	v_writelane_b32 v252, s14, 22
	v_writelane_b32 v252, s15, 23
	s_cbranch_vccz .LBB0_76
	v_readlane_b32 s68, v252, 0
	s_ashr_i32 s59, s58, 31
	v_readlane_b32 s69, v252, 1
	s_lshl_b64 s[6:7], s[58:59], 12
	s_mov_b64 s[40:41], s[68:69]
	s_add_u32 s6, s40, s6
	s_addc_u32 s7, s41, s7
	global_load_dwordx4 v[14:17], v164, s[6:7] nt
	global_load_dwordx4 v[10:13], v164, s[6:7] offset:1024 nt
	global_load_dwordx4 v[6:9], v164, s[6:7] offset:2048 nt
	global_load_dwordx4 v[2:5], v164, s[6:7] offset:3072 nt
	s_waitcnt vmcnt(7)
	v_mbcnt_hi_u32_b32 v18, -1, v38
	v_and_b32_e32 v1, 64, v18
	v_add_u32_e32 v19, 64, v1
	v_xor_b32_e32 v1, 1, v18
	v_cmp_lt_i32_e32 vcc, v1, v19
	v_xor_b32_e32 v20, 2, v18
	s_lshl_b64 s[8:9], s[58:59], 3
	v_cndmask_b32_e32 v1, v18, v1, vcc
	v_cmp_lt_i32_e32 vcc, v20, v19
	s_add_u32 s28, s8, 0x100000
	s_addc_u32 s29, s9, 0
	v_cndmask_b32_e32 v20, v18, v20, vcc
	v_lshlrev_b32_e32 v39, 2, v20
	v_xor_b32_e32 v20, 4, v18
	v_cmp_lt_i32_e32 vcc, v20, v19
	s_add_i32 s20, s58, s84
	s_ashr_i32 s85, s84, 31
	v_cndmask_b32_e32 v20, v18, v20, vcc
	v_lshlrev_b32_e32 v40, 2, v20
	v_xor_b32_e32 v20, 8, v18
	v_cmp_lt_i32_e32 vcc, v20, v19
	s_lshl_b64 s[18:19], s[58:59], 11
	s_ashr_i32 s21, s20, 31
	v_cndmask_b32_e32 v20, v18, v20, vcc
	v_lshlrev_b32_e32 v41, 2, v20
	v_xor_b32_e32 v20, 16, v18
	v_cmp_lt_i32_e32 vcc, v20, v19
	s_lshl_b64 s[8:9], s[84:85], 3
	v_lshl_or_b32 v34, v219, 3, s18
	v_cndmask_b32_e32 v20, v18, v20, vcc
	v_lshlrev_b32_e32 v42, 2, v20
	v_xor_b32_e32 v20, 32, v18
	v_mov_b32_e32 v35, s19
	s_lshl_b64 s[18:19], s[84:85], 11
	s_lshl_b64 s[20:21], s[20:21], 12
	v_cmp_lt_i32_e32 vcc, v20, v19
	s_add_u32 s20, s40, s20
	v_readlane_b32 s12, v252, 20
	v_mov_b32_e32 v165, 0
	v_cndmask_b32_e32 v18, v18, v20, vcc
	s_addc_u32 s21, s41, s21
	v_readlane_b32 s14, v252, 22
	v_readlane_b32 s15, v252, 23
	v_lshlrev_b32_e32 v1, 2, v1
	v_lshlrev_b32_e32 v43, 2, v18
	v_cmp_eq_u32_e64 s[6:7], 0, v219
	v_lshl_add_u64 v[36:37], s[20:21], 0, v[164:165]
	s_lshl_b64 s[20:21], s[84:85], 12
	s_mov_b32 s30, 0x6800000
	s_mov_b32 s31, s58
	v_readlane_b32 s70, v252, 2
	v_readlane_b32 s71, v252, 3
	v_readlane_b32 s72, v252, 4
	v_readlane_b32 s73, v252, 5
	v_readlane_b32 s74, v252, 6
	v_readlane_b32 s75, v252, 7
	v_readlane_b32 s76, v252, 8
	v_readlane_b32 s77, v252, 9
	v_readlane_b32 s78, v252, 10
	v_readlane_b32 s79, v252, 11
	v_readlane_b32 s80, v252, 12
	v_readlane_b32 s81, v252, 13
	v_readlane_b32 s82, v252, 14
	v_readlane_b32 s83, v252, 15
	v_readlane_b32 s13, v252, 21
	s_waitcnt vmcnt(0)
	s_branch .LBB0_70

.LBB0_72:
	v_mul_f32_e32 v44, v15, v15
	s_waitcnt lgkmcnt(0)
	v_mul_f32_e32 v45, v17, v17
	v_fmac_f32_e32 v44, v14, v14
	v_fmac_f32_e32 v45, v16, v16
	v_add_f32_e32 v44, v44, v45
	v_mul_f32_e32 v45, v11, v11
	v_mul_f32_e32 v46, v13, v13
	v_fmac_f32_e32 v45, v10, v10
	v_fmac_f32_e32 v46, v12, v12
	v_add_f32_e32 v45, v45, v46
	v_add_f32_e32 v44, v44, v45
	v_mul_f32_e32 v45, v7, v7
	v_mul_f32_e32 v46, v9, v9
	v_fmac_f32_e32 v45, v6, v6
	v_fmac_f32_e32 v46, v8, v8
	v_add_f32_e32 v45, v45, v46
	v_add_f32_e32 v44, v44, v45
	v_mul_f32_e32 v45, v3, v3
	v_mul_f32_e32 v46, v5, v5
	v_fmac_f32_e32 v45, v2, v2
	v_fmac_f32_e32 v46, v4, v4
	v_add_f32_e32 v45, v45, v46
	v_add_f32_e32 v44, v44, v45
	ds_bpermute_b32 v45, v1, v44
	v_lshl_add_u64 v[46:47], s[56:57], 0, v[34:35]
	v_add_co_u32_e32 v46, vcc, s30, v46
	v_cvt_pk_bf16_f32 v48, v14, v15
	s_waitcnt lgkmcnt(0)
	v_add_f32_e32 v44, v44, v45
	ds_bpermute_b32 v45, v39, v44
	v_cvt_pk_bf16_f32 v49, v16, v17
	v_addc_co_u32_e32 v47, vcc, 0, v47, vcc
	global_store_dwordx2 v[46:47], v[48:49], off
	s_waitcnt lgkmcnt(0)
	v_add_f32_e32 v44, v44, v45
	ds_bpermute_b32 v45, v40, v44
	v_cvt_pk_bf16_f32 v48, v10, v11
	v_cvt_pk_bf16_f32 v49, v12, v13
	global_store_dwordx2 v[46:47], v[48:49], off offset:512
	v_cvt_pk_bf16_f32 v48, v6, v7
	s_waitcnt lgkmcnt(0)
	v_add_f32_e32 v44, v44, v45
	ds_bpermute_b32 v45, v41, v44
	v_cvt_pk_bf16_f32 v49, v8, v9
	global_store_dwordx2 v[46:47], v[48:49], off offset:1024
	v_cvt_pk_bf16_f32 v48, v2, v3
	v_cvt_pk_bf16_f32 v49, v4, v5
	s_waitcnt lgkmcnt(0)
	v_add_f32_e32 v44, v44, v45
	ds_bpermute_b32 v45, v42, v44
	global_store_dwordx2 v[46:47], v[48:49], off offset:1536
	s_waitcnt lgkmcnt(0)
	v_add_f32_e32 v44, v44, v45
	ds_bpermute_b32 v45, v43, v44
	s_and_saveexec_b64 s[26:27], s[6:7]
	s_cbranch_execz .LBB0_74
	s_waitcnt lgkmcnt(0)
	v_add_f32_e32 v44, v44, v45
	v_mul_f32_e32 v44, 0x49800000, v44
	v_trunc_f32_e32 v44, v44
	v_mul_f32_e32 v45, 0x2f800000, v44
	v_floor_f32_e32 v45, v45
	v_fmac_f32_e32 v44, 0xcf800000, v45
	v_cvt_u32_f32_e32 v44, v44
	v_cvt_u32_f32_e32 v45, v45
	s_add_u32 s34, s56, s28
	s_addc_u32 s35, s57, s29
	global_store_dwordx2 v165, v[44:45], s[34:35]
.LBB0_74:
	s_or_b64 exec, exec, s[26:27]
	s_andn2_b64 vcc, exec, s[24:25]
	s_cbranch_vccnz .LBB0_69
	s_waitcnt vmcnt(4)
	v_mov_b64_e32 v[2:3], v[18:19]
	v_mov_b64_e32 v[6:7], v[22:23]
	v_mov_b64_e32 v[10:11], v[26:27]
	v_mov_b64_e32 v[14:15], v[30:31]
	v_mov_b64_e32 v[4:5], v[20:21]
	v_mov_b64_e32 v[8:9], v[24:25]
	v_mov_b64_e32 v[12:13], v[28:29]
	v_mov_b64_e32 v[16:17], v[32:33]
	s_branch .LBB0_69
